# up/down K-loops: MFMA order k-inner (each accumulator's k0,k1 back-to-back, serpentine over m,n) on top of p0act
# speedup vs baseline: 1.0141x; 1.0141x over previous
.LBB0_535:
	ds_read_b128 v[150:153], v128
	ds_read_b128 v[154:157], v128 offset:1024
	ds_read_b128 v[158:161], v128 offset:2048
	ds_read_b128 v[170:173], v128 offset:3072
	ds_read_b128 v[174:177], v146
	ds_read_b128 v[178:181], v146 offset:1024
	ds_read_b128 v[182:185], v146 offset:2048
	ds_read_b128 v[186:189], v146 offset:3072
	s_cmp_eq_u32 s16, 60
	s_cselect_b32 s62, s94, vcc_lo
	s_cselect_b32 s63, s53, vcc_hi
	s_cselect_b32 s60, s95, s14
	s_cselect_b32 s61, s41, s15
	s_add_u32 s58, s62, 0x8000
	s_addc_u32 s59, s63, 0
	ds_read_b128 v[190:193], v147
	ds_read_b128 v[194:197], v147 offset:1024
	ds_read_b128 v[198:201], v147 offset:2048
	ds_read_b128 v[202:205], v147 offset:3072
	ds_read_b128 v[206:209], v147 offset:4096
	ds_read_b128 v[210:213], v147 offset:5120
	ds_read_b128 v[214:217], v147 offset:6144
	ds_read_b128 v[218:221], v147 offset:7168
	s_add_u32 s18, vcc_lo, 0xffffc000
	s_addc_u32 s19, vcc_hi, -1
	s_mov_b32 m0, s89
	s_nop 0
	global_load_lds_dwordx4 v142, s[18:19]
	s_nop 0
	s_mov_b32 m0, s90
	s_nop 0
	global_load_lds_dwordx4 v144, s[18:19]
	s_waitcnt vmcnt(8)
	s_waitcnt lgkmcnt(0)
	s_setprio 1
	s_barrier
	v_mfma_f32_16x16x32_bf16 v[124:127], v[150:153], v[190:193], v[124:127]
	v_mfma_f32_16x16x32_bf16 v[124:127], v[154:157], v[194:197], v[124:127]
	v_mfma_f32_16x16x32_bf16 v[120:123], v[158:161], v[190:193], v[120:123]
	v_mfma_f32_16x16x32_bf16 v[120:123], v[170:173], v[194:197], v[120:123]
	v_mfma_f32_16x16x32_bf16 v[104:107], v[158:161], v[198:201], v[104:107]
	v_mfma_f32_16x16x32_bf16 v[104:107], v[170:173], v[202:205], v[104:107]
	v_mfma_f32_16x16x32_bf16 v[108:111], v[150:153], v[198:201], v[108:111]
	v_mfma_f32_16x16x32_bf16 v[108:111], v[154:157], v[202:205], v[108:111]
	v_mfma_f32_16x16x32_bf16 v[92:95], v[150:153], v[206:209], v[92:95]
	v_mfma_f32_16x16x32_bf16 v[92:95], v[154:157], v[210:213], v[92:95]
	v_mfma_f32_16x16x32_bf16 v[88:91], v[158:161], v[206:209], v[88:91]
	v_mfma_f32_16x16x32_bf16 v[88:91], v[170:173], v[210:213], v[88:91]
	v_mfma_f32_16x16x32_bf16 v[72:75], v[158:161], v[214:217], v[72:75]
	v_mfma_f32_16x16x32_bf16 v[72:75], v[170:173], v[218:221], v[72:75]
	v_mfma_f32_16x16x32_bf16 v[76:79], v[150:153], v[214:217], v[76:79]
	v_mfma_f32_16x16x32_bf16 v[76:79], v[154:157], v[218:221], v[76:79]
	s_setprio 0
	s_setprio 1
	v_mfma_f32_16x16x32_bf16 v[116:119], v[174:177], v[190:193], v[116:119]
	v_mfma_f32_16x16x32_bf16 v[116:119], v[178:181], v[194:197], v[116:119]
	v_mfma_f32_16x16x32_bf16 v[112:115], v[182:185], v[190:193], v[112:115]
	v_mfma_f32_16x16x32_bf16 v[112:115], v[186:189], v[194:197], v[112:115]
	v_mfma_f32_16x16x32_bf16 v[96:99], v[182:185], v[198:201], v[96:99]
	v_mfma_f32_16x16x32_bf16 v[96:99], v[186:189], v[202:205], v[96:99]
	v_mfma_f32_16x16x32_bf16 v[100:103], v[174:177], v[198:201], v[100:103]
	v_mfma_f32_16x16x32_bf16 v[100:103], v[178:181], v[202:205], v[100:103]
	v_mfma_f32_16x16x32_bf16 v[84:87], v[174:177], v[206:209], v[84:87]
	v_mfma_f32_16x16x32_bf16 v[84:87], v[178:181], v[210:213], v[84:87]
	v_mfma_f32_16x16x32_bf16 v[80:83], v[182:185], v[206:209], v[80:83]
	v_mfma_f32_16x16x32_bf16 v[80:83], v[186:189], v[210:213], v[80:83]
	v_mfma_f32_16x16x32_bf16 v[64:67], v[182:185], v[214:217], v[64:67]
	v_mfma_f32_16x16x32_bf16 v[64:67], v[186:189], v[218:221], v[64:67]
	v_mfma_f32_16x16x32_bf16 v[68:71], v[174:177], v[214:217], v[68:71]
	v_mfma_f32_16x16x32_bf16 v[68:71], v[178:181], v[218:221], v[68:71]
	s_setprio 0
	s_barrier
	ds_read_b128 v[190:193], v147 offset:16384
	ds_read_b128 v[194:197], v147 offset:17408
	ds_read_b128 v[198:201], v147 offset:18432
	ds_read_b128 v[202:205], v147 offset:19456
	ds_read_b128 v[206:209], v147 offset:20480
	ds_read_b128 v[210:213], v147 offset:21504
	ds_read_b128 v[214:217], v147 offset:22528
	ds_read_b128 v[218:221], v147 offset:23552
	s_mov_b32 m0, s45
	s_nop 0
	global_load_lds_dwordx4 v143, s[60:61]
	s_add_u32 s18, s60, 0x4000
	s_mov_b32 m0, s46
	s_nop 0
	global_load_lds_dwordx4 v145, s[60:61]
	s_addc_u32 s19, s61, 0
	s_mov_b32 m0, s47
	s_nop 0
	global_load_lds_dwordx4 v143, s[18:19]
	s_nop 0
	s_mov_b32 m0, s64
	s_nop 0
	global_load_lds_dwordx4 v145, s[18:19]
	s_nop 0
	s_mov_b32 m0, s44
	s_nop 0
	global_load_lds_dwordx4 v142, s[62:63]
	s_nop 0
	s_mov_b32 m0, s65
	s_nop 0
	global_load_lds_dwordx4 v144, s[62:63]
	s_waitcnt vmcnt(8)
	s_waitcnt lgkmcnt(0)
	s_setprio 1
	s_barrier
	v_mfma_f32_16x16x32_bf16 v[60:63], v[150:153], v[190:193], v[60:63]
	v_mfma_f32_16x16x32_bf16 v[60:63], v[154:157], v[194:197], v[60:63]
	v_mfma_f32_16x16x32_bf16 v[56:59], v[158:161], v[190:193], v[56:59]
	v_mfma_f32_16x16x32_bf16 v[56:59], v[170:173], v[194:197], v[56:59]
	v_mfma_f32_16x16x32_bf16 v[40:43], v[158:161], v[198:201], v[40:43]
	v_mfma_f32_16x16x32_bf16 v[40:43], v[170:173], v[202:205], v[40:43]
	v_mfma_f32_16x16x32_bf16 v[44:47], v[150:153], v[198:201], v[44:47]
	v_mfma_f32_16x16x32_bf16 v[44:47], v[154:157], v[202:205], v[44:47]
	v_mfma_f32_16x16x32_bf16 v[28:31], v[150:153], v[206:209], v[28:31]
	v_mfma_f32_16x16x32_bf16 v[28:31], v[154:157], v[210:213], v[28:31]
	v_mfma_f32_16x16x32_bf16 v[24:27], v[158:161], v[206:209], v[24:27]
	v_mfma_f32_16x16x32_bf16 v[24:27], v[170:173], v[210:213], v[24:27]
	v_mfma_f32_16x16x32_bf16 v[8:11], v[158:161], v[214:217], v[8:11]
	v_mfma_f32_16x16x32_bf16 v[8:11], v[170:173], v[218:221], v[8:11]
	v_mfma_f32_16x16x32_bf16 v[12:15], v[150:153], v[214:217], v[12:15]
	v_mfma_f32_16x16x32_bf16 v[12:15], v[154:157], v[218:221], v[12:15]
	s_setprio 0
	s_setprio 1
	v_mfma_f32_16x16x32_bf16 v[52:55], v[174:177], v[190:193], v[52:55]
	v_mfma_f32_16x16x32_bf16 v[52:55], v[178:181], v[194:197], v[52:55]
	v_mfma_f32_16x16x32_bf16 v[48:51], v[182:185], v[190:193], v[48:51]
	v_mfma_f32_16x16x32_bf16 v[48:51], v[186:189], v[194:197], v[48:51]
	v_mfma_f32_16x16x32_bf16 v[32:35], v[182:185], v[198:201], v[32:35]
	v_mfma_f32_16x16x32_bf16 v[32:35], v[186:189], v[202:205], v[32:35]
	v_mfma_f32_16x16x32_bf16 v[36:39], v[174:177], v[198:201], v[36:39]
	v_mfma_f32_16x16x32_bf16 v[36:39], v[178:181], v[202:205], v[36:39]
	v_mfma_f32_16x16x32_bf16 v[20:23], v[174:177], v[206:209], v[20:23]
	v_mfma_f32_16x16x32_bf16 v[20:23], v[178:181], v[210:213], v[20:23]
	v_mfma_f32_16x16x32_bf16 v[16:19], v[182:185], v[206:209], v[16:19]
	v_mfma_f32_16x16x32_bf16 v[16:19], v[186:189], v[210:213], v[16:19]
	v_mfma_f32_16x16x32_bf16 v[0:3], v[182:185], v[214:217], v[0:3]
	v_mfma_f32_16x16x32_bf16 v[0:3], v[186:189], v[218:221], v[0:3]
	v_mfma_f32_16x16x32_bf16 v[4:7], v[174:177], v[214:217], v[4:7]
	v_mfma_f32_16x16x32_bf16 v[4:7], v[178:181], v[218:221], v[4:7]
	s_setprio 0
	s_barrier
	ds_read_b128 v[150:153], v148
	ds_read_b128 v[154:157], v148 offset:1024
	ds_read_b128 v[158:161], v148 offset:2048
	ds_read_b128 v[170:173], v148 offset:3072
	ds_read_b128 v[174:177], v149
	ds_read_b128 v[178:181], v149 offset:1024
	ds_read_b128 v[182:185], v149 offset:2048
	ds_read_b128 v[186:189], v149 offset:3072
	ds_read_b128 v[190:193], v147 offset:32768
	ds_read_b128 v[194:197], v147 offset:33792
	ds_read_b128 v[198:201], v147 offset:34816
	ds_read_b128 v[202:205], v147 offset:35840
	ds_read_b128 v[206:209], v147 offset:36864
	ds_read_b128 v[210:213], v147 offset:37888
	ds_read_b128 v[214:217], v147 offset:38912
	ds_read_b128 v[218:221], v147 offset:39936
	s_add_u32 s18, s62, 0x4000
	s_addc_u32 s19, s63, 0
	s_mov_b32 m0, s66
	s_nop 0
	global_load_lds_dwordx4 v142, s[18:19]
	s_nop 0
	s_mov_b32 m0, s67
	s_nop 0
	global_load_lds_dwordx4 v144, s[18:19]
	s_waitcnt vmcnt(8)
	s_waitcnt lgkmcnt(0)
	s_setprio 1
	s_barrier
	v_mfma_f32_16x16x32_bf16 v[124:127], v[150:153], v[190:193], v[124:127]
	v_mfma_f32_16x16x32_bf16 v[124:127], v[154:157], v[194:197], v[124:127]
	v_mfma_f32_16x16x32_bf16 v[120:123], v[158:161], v[190:193], v[120:123]
	v_mfma_f32_16x16x32_bf16 v[120:123], v[170:173], v[194:197], v[120:123]
	v_mfma_f32_16x16x32_bf16 v[104:107], v[158:161], v[198:201], v[104:107]
	v_mfma_f32_16x16x32_bf16 v[104:107], v[170:173], v[202:205], v[104:107]
	v_mfma_f32_16x16x32_bf16 v[108:111], v[150:153], v[198:201], v[108:111]
	v_mfma_f32_16x16x32_bf16 v[108:111], v[154:157], v[202:205], v[108:111]
	v_mfma_f32_16x16x32_bf16 v[92:95], v[150:153], v[206:209], v[92:95]
	v_mfma_f32_16x16x32_bf16 v[92:95], v[154:157], v[210:213], v[92:95]
	v_mfma_f32_16x16x32_bf16 v[88:91], v[158:161], v[206:209], v[88:91]
	v_mfma_f32_16x16x32_bf16 v[88:91], v[170:173], v[210:213], v[88:91]
	v_mfma_f32_16x16x32_bf16 v[72:75], v[158:161], v[214:217], v[72:75]
	v_mfma_f32_16x16x32_bf16 v[72:75], v[170:173], v[218:221], v[72:75]
	v_mfma_f32_16x16x32_bf16 v[76:79], v[150:153], v[214:217], v[76:79]
	v_mfma_f32_16x16x32_bf16 v[76:79], v[154:157], v[218:221], v[76:79]
	s_setprio 0
	s_setprio 1
	v_mfma_f32_16x16x32_bf16 v[116:119], v[174:177], v[190:193], v[116:119]
	v_mfma_f32_16x16x32_bf16 v[116:119], v[178:181], v[194:197], v[116:119]
	v_mfma_f32_16x16x32_bf16 v[112:115], v[182:185], v[190:193], v[112:115]
	v_mfma_f32_16x16x32_bf16 v[112:115], v[186:189], v[194:197], v[112:115]
	v_mfma_f32_16x16x32_bf16 v[96:99], v[182:185], v[198:201], v[96:99]
	v_mfma_f32_16x16x32_bf16 v[96:99], v[186:189], v[202:205], v[96:99]
	v_mfma_f32_16x16x32_bf16 v[100:103], v[174:177], v[198:201], v[100:103]
	v_mfma_f32_16x16x32_bf16 v[100:103], v[178:181], v[202:205], v[100:103]
	v_mfma_f32_16x16x32_bf16 v[84:87], v[174:177], v[206:209], v[84:87]
	v_mfma_f32_16x16x32_bf16 v[84:87], v[178:181], v[210:213], v[84:87]
	v_mfma_f32_16x16x32_bf16 v[80:83], v[182:185], v[206:209], v[80:83]
	v_mfma_f32_16x16x32_bf16 v[80:83], v[186:189], v[210:213], v[80:83]
	v_mfma_f32_16x16x32_bf16 v[64:67], v[182:185], v[214:217], v[64:67]
	v_mfma_f32_16x16x32_bf16 v[64:67], v[186:189], v[218:221], v[64:67]
	v_mfma_f32_16x16x32_bf16 v[68:71], v[174:177], v[214:217], v[68:71]
	v_mfma_f32_16x16x32_bf16 v[68:71], v[178:181], v[218:221], v[68:71]
	s_setprio 0
	s_barrier
	ds_read_b128 v[190:193], v147 offset:49152
	ds_read_b128 v[194:197], v147 offset:50176
	ds_read_b128 v[198:201], v147 offset:51200
	ds_read_b128 v[202:205], v147 offset:52224
	ds_read_b128 v[206:209], v147 offset:53248
	ds_read_b128 v[210:213], v147 offset:54272
	ds_read_b128 v[214:217], v147 offset:55296
	ds_read_b128 v[218:221], v147 offset:56320
	s_add_u32 s18, s60, 0x8000
	s_addc_u32 s19, s61, 0
	s_mov_b32 m0, s70
	s_nop 0
	global_load_lds_dwordx4 v143, s[18:19]
	s_nop 0
	s_mov_b32 m0, s71
	s_nop 0
	global_load_lds_dwordx4 v145, s[18:19]
	s_add_u32 s18, s60, 0xc000
	s_addc_u32 s19, s61, 0
	s_mov_b32 m0, s83
	s_nop 0
	global_load_lds_dwordx4 v143, s[18:19]
	s_nop 0
	s_mov_b32 m0, s88
	s_nop 0
	global_load_lds_dwordx4 v145, s[18:19]
	s_nop 0
	s_mov_b32 m0, s72
	s_nop 0
	global_load_lds_dwordx4 v142, s[58:59]
	s_nop 0
	s_mov_b32 m0, s81
	s_nop 0
	global_load_lds_dwordx4 v144, s[58:59]
	s_waitcnt vmcnt(8)
	s_waitcnt lgkmcnt(0)
	s_setprio 1
	s_barrier
	v_mfma_f32_16x16x32_bf16 v[60:63], v[150:153], v[190:193], v[60:63]
	v_mfma_f32_16x16x32_bf16 v[60:63], v[154:157], v[194:197], v[60:63]
	v_mfma_f32_16x16x32_bf16 v[56:59], v[158:161], v[190:193], v[56:59]
	v_mfma_f32_16x16x32_bf16 v[56:59], v[170:173], v[194:197], v[56:59]
	v_mfma_f32_16x16x32_bf16 v[40:43], v[158:161], v[198:201], v[40:43]
	v_mfma_f32_16x16x32_bf16 v[40:43], v[170:173], v[202:205], v[40:43]
	v_mfma_f32_16x16x32_bf16 v[44:47], v[150:153], v[198:201], v[44:47]
	v_mfma_f32_16x16x32_bf16 v[44:47], v[154:157], v[202:205], v[44:47]
	v_mfma_f32_16x16x32_bf16 v[28:31], v[150:153], v[206:209], v[28:31]
	v_mfma_f32_16x16x32_bf16 v[28:31], v[154:157], v[210:213], v[28:31]
	v_mfma_f32_16x16x32_bf16 v[24:27], v[158:161], v[206:209], v[24:27]
	v_mfma_f32_16x16x32_bf16 v[24:27], v[170:173], v[210:213], v[24:27]
	v_mfma_f32_16x16x32_bf16 v[8:11], v[158:161], v[214:217], v[8:11]
	v_mfma_f32_16x16x32_bf16 v[8:11], v[170:173], v[218:221], v[8:11]
	v_mfma_f32_16x16x32_bf16 v[12:15], v[150:153], v[214:217], v[12:15]
	v_mfma_f32_16x16x32_bf16 v[12:15], v[154:157], v[218:221], v[12:15]
	s_setprio 0
	s_setprio 1
	v_mfma_f32_16x16x32_bf16 v[52:55], v[174:177], v[190:193], v[52:55]
	v_mfma_f32_16x16x32_bf16 v[52:55], v[178:181], v[194:197], v[52:55]
	v_mfma_f32_16x16x32_bf16 v[48:51], v[182:185], v[190:193], v[48:51]
	v_mfma_f32_16x16x32_bf16 v[48:51], v[186:189], v[194:197], v[48:51]
	v_mfma_f32_16x16x32_bf16 v[32:35], v[182:185], v[198:201], v[32:35]
	v_mfma_f32_16x16x32_bf16 v[32:35], v[186:189], v[202:205], v[32:35]
	v_mfma_f32_16x16x32_bf16 v[36:39], v[174:177], v[198:201], v[36:39]
	v_mfma_f32_16x16x32_bf16 v[36:39], v[178:181], v[202:205], v[36:39]
	v_mfma_f32_16x16x32_bf16 v[20:23], v[174:177], v[206:209], v[20:23]
	v_mfma_f32_16x16x32_bf16 v[20:23], v[178:181], v[210:213], v[20:23]
	v_mfma_f32_16x16x32_bf16 v[16:19], v[182:185], v[206:209], v[16:19]
	v_mfma_f32_16x16x32_bf16 v[16:19], v[186:189], v[210:213], v[16:19]
	v_mfma_f32_16x16x32_bf16 v[0:3], v[182:185], v[214:217], v[0:3]
	v_mfma_f32_16x16x32_bf16 v[0:3], v[186:189], v[218:221], v[0:3]
	v_mfma_f32_16x16x32_bf16 v[4:7], v[174:177], v[214:217], v[4:7]
	v_mfma_f32_16x16x32_bf16 v[4:7], v[178:181], v[218:221], v[4:7]
	s_setprio 0
	s_barrier
	s_add_i32 s16, s16, 2
	s_add_u32 vcc_lo, vcc_lo, 0x10000
	s_addc_u32 vcc_hi, vcc_hi, 0
	s_add_u32 s14, s14, 0x10000
	s_addc_u32 s15, s15, 0
	s_cmp_gt_u32 s16, 61
	s_cbranch_scc0 .LBB0_535
	s_and_b64 vcc, exec, s[48:49]
	s_cbranch_vccz .LBB0_538
	s_barrier

.LBB0_618:
	v_add_u32_e32 v164, 0x10000, v179
	ds_read_b128 v[182:185], v164
	ds_read_b128 v[186:189], v164 offset:1024
	ds_read_b128 v[190:193], v164 offset:2048
	ds_read_b128 v[194:197], v164 offset:3072
	v_add_u32_e32 v164, 0x14000, v179
	ds_read_b128 v[198:201], v164
	ds_read_b128 v[202:205], v164 offset:1024
	ds_read_b128 v[206:209], v164 offset:2048
	ds_read_b128 v[210:213], v164 offset:3072
	s_cmpk_eq_i32 s18, 0xfc
	s_cselect_b32 s66, s16, s55
	s_cselect_b32 s67, s15, s61
	s_cselect_b32 s64, s17, vcc_lo
	s_cselect_b32 s65, s11, vcc_hi
	s_add_u32 s62, s66, 0x8000
	s_addc_u32 s63, s67, 0
	ds_read_b128 v[214:217], v180
	ds_read_b128 v[218:221], v180 offset:1024
	ds_read_b128 v[222:225], v180 offset:2048
	ds_read_b128 v[226:229], v180 offset:3072
	ds_read_b128 v[230:233], v180 offset:4096
	ds_read_b128 v[234:237], v180 offset:5120
	ds_read_b128 v[238:241], v180 offset:6144
	ds_read_b128 v[242:245], v180 offset:7168
	s_add_u32 s28, s55, 0xffffc000
	s_addc_u32 s29, s61, -1
	s_mov_b32 m0, s47
	s_nop 0
	global_load_lds_dwordx4 v176, s[28:29]
	s_nop 0
	s_mov_b32 m0, s94
	s_nop 0
	global_load_lds_dwordx4 v177, s[28:29]
	s_waitcnt vmcnt(8)
	s_waitcnt lgkmcnt(0)
	s_setprio 1
	s_barrier
	v_mfma_f32_16x16x32_bf16 v[0:3], v[182:185], v[214:217], v[0:3]
	v_mfma_f32_16x16x32_bf16 v[0:3], v[186:189], v[218:221], v[0:3]
	v_mfma_f32_16x16x32_bf16 v[4:7], v[190:193], v[214:217], v[4:7]
	v_mfma_f32_16x16x32_bf16 v[4:7], v[194:197], v[218:221], v[4:7]
	v_mfma_f32_16x16x32_bf16 v[24:27], v[190:193], v[222:225], v[24:27]
	v_mfma_f32_16x16x32_bf16 v[24:27], v[194:197], v[226:229], v[24:27]
	v_mfma_f32_16x16x32_bf16 v[12:15], v[182:185], v[222:225], v[12:15]
	v_mfma_f32_16x16x32_bf16 v[12:15], v[186:189], v[226:229], v[12:15]
	v_mfma_f32_16x16x32_bf16 v[44:47], v[182:185], v[230:233], v[44:47]
	v_mfma_f32_16x16x32_bf16 v[44:47], v[186:189], v[234:237], v[44:47]
	v_mfma_f32_16x16x32_bf16 v[56:59], v[190:193], v[230:233], v[56:59]
	v_mfma_f32_16x16x32_bf16 v[56:59], v[194:197], v[234:237], v[56:59]
	v_mfma_f32_16x16x32_bf16 v[80:83], v[190:193], v[238:241], v[80:83]
	v_mfma_f32_16x16x32_bf16 v[80:83], v[194:197], v[242:245], v[80:83]
	v_mfma_f32_16x16x32_bf16 v[68:71], v[182:185], v[238:241], v[68:71]
	v_mfma_f32_16x16x32_bf16 v[68:71], v[186:189], v[242:245], v[68:71]
	s_setprio 0
	s_setprio 1
	v_mfma_f32_16x16x32_bf16 v[20:23], v[198:201], v[214:217], v[20:23]
	v_mfma_f32_16x16x32_bf16 v[20:23], v[202:205], v[218:221], v[20:23]
	v_mfma_f32_16x16x32_bf16 v[36:39], v[206:209], v[214:217], v[36:39]
	v_mfma_f32_16x16x32_bf16 v[36:39], v[210:213], v[218:221], v[36:39]
	v_mfma_f32_16x16x32_bf16 v[60:63], v[206:209], v[222:225], v[60:63]
	v_mfma_f32_16x16x32_bf16 v[60:63], v[210:213], v[226:229], v[60:63]
	v_mfma_f32_16x16x32_bf16 v[48:51], v[198:201], v[222:225], v[48:51]
	v_mfma_f32_16x16x32_bf16 v[48:51], v[202:205], v[226:229], v[48:51]
	v_mfma_f32_16x16x32_bf16 v[72:75], v[198:201], v[230:233], v[72:75]
	v_mfma_f32_16x16x32_bf16 v[72:75], v[202:205], v[234:237], v[72:75]
	v_mfma_f32_16x16x32_bf16 v[88:91], v[206:209], v[230:233], v[88:91]
	v_mfma_f32_16x16x32_bf16 v[88:91], v[210:213], v[234:237], v[88:91]
	v_mfma_f32_16x16x32_bf16 v[104:107], v[206:209], v[238:241], v[104:107]
	v_mfma_f32_16x16x32_bf16 v[104:107], v[210:213], v[242:245], v[104:107]
	v_mfma_f32_16x16x32_bf16 v[96:99], v[198:201], v[238:241], v[96:99]
	v_mfma_f32_16x16x32_bf16 v[96:99], v[202:205], v[242:245], v[96:99]
	s_setprio 0
	s_barrier
	ds_read_b128 v[214:217], v180 offset:16384
	ds_read_b128 v[218:221], v180 offset:17408
	ds_read_b128 v[222:225], v180 offset:18432
	ds_read_b128 v[226:229], v180 offset:19456
	ds_read_b128 v[230:233], v180 offset:20480
	ds_read_b128 v[234:237], v180 offset:21504
	ds_read_b128 v[238:241], v180 offset:22528
	ds_read_b128 v[242:245], v180 offset:23552
	s_mov_b32 m0, s8
	s_nop 0
	global_load_lds_dwordx4 v176, s[64:65]
	s_add_u32 s28, s64, 0x4000
	s_mov_b32 m0, s20
	s_nop 0
	global_load_lds_dwordx4 v177, s[64:65]
	s_addc_u32 s29, s65, 0
	s_mov_b32 m0, s22
	s_nop 0
	global_load_lds_dwordx4 v176, s[28:29]
	s_nop 0
	s_mov_b32 m0, s24
	s_nop 0
	global_load_lds_dwordx4 v177, s[28:29]
	s_nop 0
	s_mov_b32 m0, s83
	s_nop 0
	global_load_lds_dwordx4 v176, s[66:67]
	s_nop 0
	s_mov_b32 m0, s25
	s_nop 0
	global_load_lds_dwordx4 v177, s[66:67]
	s_waitcnt vmcnt(8)
	s_waitcnt lgkmcnt(0)
	s_setprio 1
	s_barrier
	v_mfma_f32_16x16x32_bf16 v[28:31], v[182:185], v[214:217], v[28:31]
	v_mfma_f32_16x16x32_bf16 v[28:31], v[186:189], v[218:221], v[28:31]
	v_mfma_f32_16x16x32_bf16 v[8:11], v[190:193], v[214:217], v[8:11]
	v_mfma_f32_16x16x32_bf16 v[8:11], v[194:197], v[218:221], v[8:11]
	v_mfma_f32_16x16x32_bf16 v[52:55], v[190:193], v[222:225], v[52:55]
	v_mfma_f32_16x16x32_bf16 v[52:55], v[194:197], v[226:229], v[52:55]
	v_mfma_f32_16x16x32_bf16 v[40:43], v[182:185], v[222:225], v[40:43]
	v_mfma_f32_16x16x32_bf16 v[40:43], v[186:189], v[226:229], v[40:43]
	v_mfma_f32_16x16x32_bf16 v[84:87], v[182:185], v[230:233], v[84:87]
	v_mfma_f32_16x16x32_bf16 v[84:87], v[186:189], v[234:237], v[84:87]
	v_mfma_f32_16x16x32_bf16 v[92:95], v[190:193], v[230:233], v[92:95]
	v_mfma_f32_16x16x32_bf16 v[92:95], v[194:197], v[234:237], v[92:95]
	v_mfma_f32_16x16x32_bf16 v[116:119], v[190:193], v[238:241], v[116:119]
	v_mfma_f32_16x16x32_bf16 v[116:119], v[194:197], v[242:245], v[116:119]
	v_mfma_f32_16x16x32_bf16 v[112:115], v[182:185], v[238:241], v[112:115]
	v_mfma_f32_16x16x32_bf16 v[112:115], v[186:189], v[242:245], v[112:115]
	s_setprio 0
	s_setprio 1
	v_mfma_f32_16x16x32_bf16 v[16:19], v[198:201], v[214:217], v[16:19]
	v_mfma_f32_16x16x32_bf16 v[16:19], v[202:205], v[218:221], v[16:19]
	v_mfma_f32_16x16x32_bf16 v[32:35], v[206:209], v[214:217], v[32:35]
	v_mfma_f32_16x16x32_bf16 v[32:35], v[210:213], v[218:221], v[32:35]
	v_mfma_f32_16x16x32_bf16 v[76:79], v[206:209], v[222:225], v[76:79]
	v_mfma_f32_16x16x32_bf16 v[76:79], v[210:213], v[226:229], v[76:79]
	v_mfma_f32_16x16x32_bf16 v[64:67], v[198:201], v[222:225], v[64:67]
	v_mfma_f32_16x16x32_bf16 v[64:67], v[202:205], v[226:229], v[64:67]
	v_mfma_f32_16x16x32_bf16 v[100:103], v[198:201], v[230:233], v[100:103]
	v_mfma_f32_16x16x32_bf16 v[100:103], v[202:205], v[234:237], v[100:103]
	v_mfma_f32_16x16x32_bf16 v[108:111], v[206:209], v[230:233], v[108:111]
	v_mfma_f32_16x16x32_bf16 v[108:111], v[210:213], v[234:237], v[108:111]
	v_mfma_f32_16x16x32_bf16 v[124:127], v[206:209], v[238:241], v[124:127]
	v_mfma_f32_16x16x32_bf16 v[124:127], v[210:213], v[242:245], v[124:127]
	v_mfma_f32_16x16x32_bf16 v[120:123], v[198:201], v[238:241], v[120:123]
	v_mfma_f32_16x16x32_bf16 v[120:123], v[202:205], v[242:245], v[120:123]
	s_setprio 0
	s_barrier
	v_add_u32_e32 v164, 0x18000, v179
	ds_read_b128 v[182:185], v164
	ds_read_b128 v[186:189], v164 offset:1024
	ds_read_b128 v[190:193], v164 offset:2048
	ds_read_b128 v[194:197], v164 offset:3072
	v_add_u32_e32 v164, 0x1c000, v179
	ds_read_b128 v[198:201], v164
	ds_read_b128 v[202:205], v164 offset:1024
	ds_read_b128 v[206:209], v164 offset:2048
	ds_read_b128 v[210:213], v164 offset:3072
	ds_read_b128 v[214:217], v180 offset:32768
	ds_read_b128 v[218:221], v180 offset:33792
	ds_read_b128 v[222:225], v180 offset:34816
	ds_read_b128 v[226:229], v180 offset:35840
	ds_read_b128 v[230:233], v180 offset:36864
	ds_read_b128 v[234:237], v180 offset:37888
	ds_read_b128 v[238:241], v180 offset:38912
	ds_read_b128 v[242:245], v180 offset:39936
	s_add_u32 s28, s66, 0x4000
	s_addc_u32 s29, s67, 0
	s_mov_b32 m0, s4
	s_nop 0
	global_load_lds_dwordx4 v176, s[28:29]
	s_nop 0
	s_mov_b32 m0, s5
	s_nop 0
	global_load_lds_dwordx4 v177, s[28:29]
	s_waitcnt vmcnt(8)
	s_waitcnt lgkmcnt(0)
	s_setprio 1
	s_barrier
	v_mfma_f32_16x16x32_bf16 v[0:3], v[182:185], v[214:217], v[0:3]
	v_mfma_f32_16x16x32_bf16 v[0:3], v[186:189], v[218:221], v[0:3]
	v_mfma_f32_16x16x32_bf16 v[4:7], v[190:193], v[214:217], v[4:7]
	v_mfma_f32_16x16x32_bf16 v[4:7], v[194:197], v[218:221], v[4:7]
	v_mfma_f32_16x16x32_bf16 v[24:27], v[190:193], v[222:225], v[24:27]
	v_mfma_f32_16x16x32_bf16 v[24:27], v[194:197], v[226:229], v[24:27]
	v_mfma_f32_16x16x32_bf16 v[12:15], v[182:185], v[222:225], v[12:15]
	v_mfma_f32_16x16x32_bf16 v[12:15], v[186:189], v[226:229], v[12:15]
	v_mfma_f32_16x16x32_bf16 v[44:47], v[182:185], v[230:233], v[44:47]
	v_mfma_f32_16x16x32_bf16 v[44:47], v[186:189], v[234:237], v[44:47]
	v_mfma_f32_16x16x32_bf16 v[56:59], v[190:193], v[230:233], v[56:59]
	v_mfma_f32_16x16x32_bf16 v[56:59], v[194:197], v[234:237], v[56:59]
	v_mfma_f32_16x16x32_bf16 v[80:83], v[190:193], v[238:241], v[80:83]
	v_mfma_f32_16x16x32_bf16 v[80:83], v[194:197], v[242:245], v[80:83]
	v_mfma_f32_16x16x32_bf16 v[68:71], v[182:185], v[238:241], v[68:71]
	v_mfma_f32_16x16x32_bf16 v[68:71], v[186:189], v[242:245], v[68:71]
	s_setprio 0
	s_setprio 1
	v_mfma_f32_16x16x32_bf16 v[20:23], v[198:201], v[214:217], v[20:23]
	v_mfma_f32_16x16x32_bf16 v[20:23], v[202:205], v[218:221], v[20:23]
	v_mfma_f32_16x16x32_bf16 v[36:39], v[206:209], v[214:217], v[36:39]
	v_mfma_f32_16x16x32_bf16 v[36:39], v[210:213], v[218:221], v[36:39]
	v_mfma_f32_16x16x32_bf16 v[60:63], v[206:209], v[222:225], v[60:63]
	v_mfma_f32_16x16x32_bf16 v[60:63], v[210:213], v[226:229], v[60:63]
	v_mfma_f32_16x16x32_bf16 v[48:51], v[198:201], v[222:225], v[48:51]
	v_mfma_f32_16x16x32_bf16 v[48:51], v[202:205], v[226:229], v[48:51]
	v_mfma_f32_16x16x32_bf16 v[72:75], v[198:201], v[230:233], v[72:75]
	v_mfma_f32_16x16x32_bf16 v[72:75], v[202:205], v[234:237], v[72:75]
	v_mfma_f32_16x16x32_bf16 v[88:91], v[206:209], v[230:233], v[88:91]
	v_mfma_f32_16x16x32_bf16 v[88:91], v[210:213], v[234:237], v[88:91]
	v_mfma_f32_16x16x32_bf16 v[104:107], v[206:209], v[238:241], v[104:107]
	v_mfma_f32_16x16x32_bf16 v[104:107], v[210:213], v[242:245], v[104:107]
	v_mfma_f32_16x16x32_bf16 v[96:99], v[198:201], v[238:241], v[96:99]
	v_mfma_f32_16x16x32_bf16 v[96:99], v[202:205], v[242:245], v[96:99]
	s_setprio 0
	s_barrier
	ds_read_b128 v[214:217], v180 offset:49152
	ds_read_b128 v[218:221], v180 offset:50176
	ds_read_b128 v[222:225], v180 offset:51200
	ds_read_b128 v[226:229], v180 offset:52224
	ds_read_b128 v[230:233], v180 offset:53248
	ds_read_b128 v[234:237], v180 offset:54272
	ds_read_b128 v[238:241], v180 offset:55296
	ds_read_b128 v[242:245], v180 offset:56320
	s_add_u32 s28, s64, 0x8000
	s_addc_u32 s29, s65, 0
	s_mov_b32 m0, s70
	s_nop 0
	global_load_lds_dwordx4 v176, s[28:29]
	s_nop 0
	s_mov_b32 m0, s71
	s_nop 0
	global_load_lds_dwordx4 v177, s[28:29]
	s_add_u32 s28, s64, 0xc000
	s_addc_u32 s29, s65, 0
	s_mov_b32 m0, s45
	s_nop 0
	global_load_lds_dwordx4 v176, s[28:29]
	s_nop 0
	s_mov_b32 m0, s46
	s_nop 0
	global_load_lds_dwordx4 v177, s[28:29]
	s_nop 0
	s_mov_b32 m0, s72
	s_nop 0
	global_load_lds_dwordx4 v176, s[62:63]
	s_nop 0
	s_mov_b32 m0, s44
	s_nop 0
	global_load_lds_dwordx4 v177, s[62:63]
	s_waitcnt vmcnt(8)
	s_waitcnt lgkmcnt(0)
	s_setprio 1
	s_barrier
	v_mfma_f32_16x16x32_bf16 v[28:31], v[182:185], v[214:217], v[28:31]
	v_mfma_f32_16x16x32_bf16 v[28:31], v[186:189], v[218:221], v[28:31]
	v_mfma_f32_16x16x32_bf16 v[8:11], v[190:193], v[214:217], v[8:11]
	v_mfma_f32_16x16x32_bf16 v[8:11], v[194:197], v[218:221], v[8:11]
	v_mfma_f32_16x16x32_bf16 v[52:55], v[190:193], v[222:225], v[52:55]
	v_mfma_f32_16x16x32_bf16 v[52:55], v[194:197], v[226:229], v[52:55]
	v_mfma_f32_16x16x32_bf16 v[40:43], v[182:185], v[222:225], v[40:43]
	v_mfma_f32_16x16x32_bf16 v[40:43], v[186:189], v[226:229], v[40:43]
	v_mfma_f32_16x16x32_bf16 v[84:87], v[182:185], v[230:233], v[84:87]
	v_mfma_f32_16x16x32_bf16 v[84:87], v[186:189], v[234:237], v[84:87]
	v_mfma_f32_16x16x32_bf16 v[92:95], v[190:193], v[230:233], v[92:95]
	v_mfma_f32_16x16x32_bf16 v[92:95], v[194:197], v[234:237], v[92:95]
	v_mfma_f32_16x16x32_bf16 v[116:119], v[190:193], v[238:241], v[116:119]
	v_mfma_f32_16x16x32_bf16 v[116:119], v[194:197], v[242:245], v[116:119]
	v_mfma_f32_16x16x32_bf16 v[112:115], v[182:185], v[238:241], v[112:115]
	v_mfma_f32_16x16x32_bf16 v[112:115], v[186:189], v[242:245], v[112:115]
	s_setprio 0
	s_setprio 1
	v_mfma_f32_16x16x32_bf16 v[16:19], v[198:201], v[214:217], v[16:19]
	v_mfma_f32_16x16x32_bf16 v[16:19], v[202:205], v[218:221], v[16:19]
	v_mfma_f32_16x16x32_bf16 v[32:35], v[206:209], v[214:217], v[32:35]
	v_mfma_f32_16x16x32_bf16 v[32:35], v[210:213], v[218:221], v[32:35]
	v_mfma_f32_16x16x32_bf16 v[76:79], v[206:209], v[222:225], v[76:79]
	v_mfma_f32_16x16x32_bf16 v[76:79], v[210:213], v[226:229], v[76:79]
	v_mfma_f32_16x16x32_bf16 v[64:67], v[198:201], v[222:225], v[64:67]
	v_mfma_f32_16x16x32_bf16 v[64:67], v[202:205], v[226:229], v[64:67]
	v_mfma_f32_16x16x32_bf16 v[100:103], v[198:201], v[230:233], v[100:103]
	v_mfma_f32_16x16x32_bf16 v[100:103], v[202:205], v[234:237], v[100:103]
	v_mfma_f32_16x16x32_bf16 v[108:111], v[206:209], v[230:233], v[108:111]
	v_mfma_f32_16x16x32_bf16 v[108:111], v[210:213], v[234:237], v[108:111]
	v_mfma_f32_16x16x32_bf16 v[124:127], v[206:209], v[238:241], v[124:127]
	v_mfma_f32_16x16x32_bf16 v[124:127], v[210:213], v[242:245], v[124:127]
	v_mfma_f32_16x16x32_bf16 v[120:123], v[198:201], v[238:241], v[120:123]
	v_mfma_f32_16x16x32_bf16 v[120:123], v[202:205], v[242:245], v[120:123]
	s_setprio 0
	s_barrier
	s_add_i32 s18, s18, 2
	s_add_u32 s55, s55, 0x10000
	s_addc_u32 s61, s61, 0
	s_add_u32 vcc_lo, vcc_lo, 0x10000
	s_addc_u32 vcc_hi, vcc_hi, 0
	s_cmpk_gt_u32 s18, 0xfd
	s_cbranch_scc0 .LBB0_618
	s_and_b64 vcc, exec, s[48:49]
	s_cbranch_vccz .LBB0_621
	s_barrier
	s_andn2_b64 vcc, exec, s[36:37]
	s_cbranch_vccnz .LBB0_623
	s_branch .LBB0_622
